# rec_pass1: LDS reads hoisted in all read-only (sub-)blocks, private address adds dropped where the read overwrites them
# speedup vs baseline: 1.0051x; 1.0051x over previous
.LBB0_200:
	s_or_b64 exec, exec, s[2:3]
	s_movk_i32 s2, 0x840
	v_mad_u32_u24 v12, v108, s2, v105
	v_add_u32_e32 v4, 0xffffff7c, v12
	v_cmp_eq_u32_e64 s[36:37], 0, v108
	v_cmp_ne_u32_e32 vcc, 0, v108
	v_mov_b32_e32 v25, 0
	v_lshl_add_u32 v14, v15, 2, v4
	v_mov_b32_e32 v26, 0
	s_and_saveexec_b64 s[2:3], vcc
	ds_read_b32 v26, v14
	s_or_b64 exec, exec, s[2:3]
	v_lshlrev_b32_e32 v13, 2, v15
	s_and_saveexec_b64 s[2:3], vcc
	s_movk_i32 s4, 0xff80
	v_add3_u32 v4, v12, v13, s4
	ds_read_b32 v25, v4
	s_or_b64 exec, exec, s[2:3]
	v_mul_u32_u24_e32 v4, 0x84, v110
	v_add3_u32 v11, v105, v4, v13
	ds_read2_b32 v[4:5], v11 offset1:1
	v_mov_b32_e32 v27, 0
	v_mov_b32_e32 v28, 0
	s_and_saveexec_b64 s[2:3], vcc
	ds_read_b32 v28, v14 offset:8
	s_or_b64 exec, exec, s[2:3]
	s_and_saveexec_b64 s[2:3], vcc
	s_movk_i32 s4, 0xff88
	v_add3_u32 v6, v12, v13, s4
	ds_read_b32 v27, v6
	s_or_b64 exec, exec, s[2:3]
	ds_read2_b32 v[6:7], v11 offset0:2 offset1:3
	v_mov_b32_e32 v20, 0
	v_mov_b32_e32 v21, 0
	s_and_saveexec_b64 s[2:3], vcc
	ds_read_b32 v21, v14 offset:16
	s_or_b64 exec, exec, s[2:3]
	s_and_saveexec_b64 s[2:3], vcc
	s_movk_i32 s4, 0xff90
	v_add3_u32 v8, v12, v13, s4
	ds_read_b32 v20, v8
	s_or_b64 exec, exec, s[2:3]
	ds_read2_b32 v[8:9], v11 offset0:4 offset1:5
	v_mov_b32_e32 v22, 0
	v_mov_b32_e32 v23, 0
	s_and_saveexec_b64 s[2:3], vcc
	ds_read_b32 v23, v14 offset:24
	s_or_b64 exec, exec, s[2:3]
	s_and_saveexec_b64 s[2:3], vcc
	s_movk_i32 s4, 0xff98
	v_add3_u32 v12, v12, v13, s4
	ds_read_b32 v22, v12
	s_or_b64 exec, exec, s[2:3]
	s_waitcnt lgkmcnt(2)
	v_sub_f32_e32 v12, v4, v26
	v_sub_f32_e32 v13, v5, v25
	v_mul_f32_e32 v4, 0x3fb8aa3b, v4
	v_mul_f32_e32 v5, 0x3fb8aa3b, v5
	v_exp_f32_e32 v4, v4
	v_exp_f32_e32 v5, v5
	v_mul_f32_e32 v12, 0x3fb8aa3b, v12
	v_mul_f32_e32 v13, 0x3fb8aa3b, v13
	v_exp_f32_e32 v12, v12
	v_exp_f32_e32 v13, v13
	v_lshlrev_b32_e32 v16, 16, v0
	v_and_b32_e32 v17, 0xffff0000, v0
	s_mov_b32 s2, 0x3e3504f3
	v_pk_mul_f32 v[16:17], v[16:17], s[2:3] op_sel_hi:[1,0]
	s_movk_i32 s4, 0x300
	v_pk_mul_f32 v[4:5], v[16:17], v[4:5]
	v_pk_mul_f32 v[12:13], v[16:17], v[12:13]
	v_cvt_pk_bf16_f32 v4, v4, v5
	s_waitcnt lgkmcnt(1)
	v_sub_f32_e32 v5, v6, v28
	v_mul_f32_e32 v5, 0x3fb8aa3b, v5
	v_cvt_pk_bf16_f32 v0, v12, v13
	v_exp_f32_e32 v12, v5
	v_sub_f32_e32 v5, v7, v27
	v_mul_f32_e32 v5, 0x3fb8aa3b, v5
	v_exp_f32_e32 v13, v5
	v_mul_f32_e32 v5, 0x3fb8aa3b, v6
	v_exp_f32_e32 v6, v5
	v_mul_f32_e32 v5, 0x3fb8aa3b, v7
	v_exp_f32_e32 v7, v5
	v_lshlrev_b32_e32 v16, 16, v1
	v_and_b32_e32 v17, 0xffff0000, v1
	v_pk_mul_f32 v[16:17], v[16:17], s[2:3] op_sel_hi:[1,0]
	v_or_b32_e32 v31, 2, v24
	v_pk_mul_f32 v[6:7], v[16:17], v[6:7]
	v_pk_mul_f32 v[12:13], v[16:17], v[12:13]
	v_cvt_pk_bf16_f32 v5, v6, v7
	s_waitcnt lgkmcnt(0)
	v_sub_f32_e32 v6, v8, v21
	v_sub_f32_e32 v7, v9, v20
	v_mul_f32_e32 v6, 0x3fb8aa3b, v6
	v_mul_f32_e32 v7, 0x3fb8aa3b, v7
	v_exp_f32_e32 v6, v6
	v_exp_f32_e32 v7, v7
	v_mul_f32_e32 v8, 0x3fb8aa3b, v8
	v_mul_f32_e32 v9, 0x3fb8aa3b, v9
	v_exp_f32_e32 v8, v8
	v_exp_f32_e32 v9, v9
	v_cvt_pk_bf16_f32 v1, v12, v13
	v_lshlrev_b32_e32 v12, 16, v2
	v_and_b32_e32 v13, 0xffff0000, v2
	v_pk_mul_f32 v[12:13], v[12:13], s[2:3] op_sel_hi:[1,0]
	v_lshlrev_b32_e32 v16, 16, v3
	v_pk_mul_f32 v[6:7], v[12:13], v[6:7]
	v_and_b32_e32 v17, 0xffff0000, v3
	v_cvt_pk_bf16_f32 v2, v6, v7
	v_pk_mul_f32 v[6:7], v[12:13], v[8:9]
	ds_read2_b32 v[8:9], v11 offset0:6 offset1:7
	v_cvt_pk_bf16_f32 v6, v6, v7
	v_pk_mul_f32 v[16:17], v[16:17], s[2:3] op_sel_hi:[1,0]
	v_or_b32_e32 v30, 3, v24
	s_waitcnt lgkmcnt(0)
	v_sub_f32_e32 v7, v8, v23
	v_mul_f32_e32 v7, 0x3fb8aa3b, v7
	v_exp_f32_e32 v12, v7
	v_sub_f32_e32 v7, v9, v22
	v_mul_f32_e32 v7, 0x3fb8aa3b, v7
	v_exp_f32_e32 v13, v7
	v_mul_f32_e32 v7, 0x3fb8aa3b, v8
	v_exp_f32_e32 v8, v7
	v_mul_f32_e32 v7, 0x3fb8aa3b, v9
	v_exp_f32_e32 v9, v7
	v_pk_mul_f32 v[12:13], v[16:17], v[12:13]
	v_pk_mul_f32 v[8:9], v[16:17], v[8:9]
	s_nop 0
	v_cvt_pk_bf16_f32 v7, v8, v9
	v_mov_b64_e32 v[8:9], s[68:69]
	v_mad_u64_u32 v[8:9], s[2:3], v100, s4, v[8:9]
	v_cvt_pk_bf16_f32 v3, v12, v13
	v_mov_b32_e32 v12, v9
	v_mad_u64_u32 v[12:13], s[2:3], v101, s4, v[12:13]
	v_mov_b32_e32 v9, v12
	v_lshlrev_b32_e32 v12, 1, v109
	v_mov_b32_e32 v13, v177
	v_lshl_add_u64 v[8:9], v[8:9], 0, v[12:13]
	v_lshlrev_b32_e32 v12, 1, v15
	v_lshl_add_u64 v[8:9], v[8:9], 0, v[12:13]
	s_mov_b32 s2, 0xece4000
	v_add_co_u32_e64 v8, s[38:39], s2, v8
	s_nop 1
	v_addc_co_u32_e64 v9, s[38:39], 0, v9, s[38:39]
	global_store_dwordx4 v[8:9], v[4:7], off offset:512 sc1
	s_nop 1
	v_mad_u32_u24 v4, v107, 33, v15
	v_lshl_add_u32 v29, v4, 2, v105
	ds_read2_b32 v[200:201], v29 offset1:1
	v_add_u32_e32 v199, 0x4400, v29
	ds_read2_b32 v[202:203], v199 offset1:1
	ds_read2_b32 v[204:205], v29 offset0:2 offset1:3
	v_add_u32_e32 v222, 0x4408, v29
	ds_read2_b32 v[220:221], v222 offset1:1
	ds_read2_b32 v[224:225], v29 offset0:4 offset1:5
	v_add_u32_e32 v223, 0x4410, v29
	ds_read2_b32 v[226:227], v223 offset1:1
	ds_read2_b32 v[228:229], v29 offset0:6 offset1:7
	v_add_u32_e32 v232, 0x4418, v29
	ds_read2_b32 v[230:231], v232 offset1:1
	s_waitcnt lgkmcnt(1)
	v_sub_f32_e32 v4, v26, v200
	v_sub_f32_e32 v5, v25, v201
	v_min_f32_e32 v4, 0x42a00000, v4
	v_min_f32_e32 v5, 0x42a00000, v5
	v_mul_f32_e32 v4, 0x3fb8aa3b, v4
	v_mul_f32_e32 v5, 0x3fb8aa3b, v5
	v_exp_f32_e32 v4, v4
	v_exp_f32_e32 v5, v5
	s_waitcnt lgkmcnt(0)
	v_pk_mul_f32 v[4:5], v[202:203], v[4:5]
	v_cvt_pk_bf16_f32 v4, v4, v5
	v_add_u32_e32 v5, 0x4408, v29
	s_waitcnt lgkmcnt(1)
	v_sub_f32_e32 v6, v28, v204
	v_sub_f32_e32 v7, v27, v205
	v_min_f32_e32 v6, 0x42a00000, v6
	v_min_f32_e32 v7, 0x42a00000, v7
	v_mul_f32_e32 v6, 0x3fb8aa3b, v6
	v_mul_f32_e32 v7, 0x3fb8aa3b, v7
	v_exp_f32_e32 v6, v6
	v_exp_f32_e32 v7, v7
	s_waitcnt lgkmcnt(0)
	v_pk_mul_f32 v[6:7], v[220:221], v[6:7]
	s_nop 0
	v_cvt_pk_bf16_f32 v5, v6, v7
	s_waitcnt lgkmcnt(1)
	v_sub_f32_e32 v6, v21, v224
	v_sub_f32_e32 v7, v20, v225
	v_min_f32_e32 v6, 0x42a00000, v6
	v_min_f32_e32 v7, 0x42a00000, v7
	v_mul_f32_e32 v6, 0x3fb8aa3b, v6
	v_mul_f32_e32 v7, 0x3fb8aa3b, v7
	v_exp_f32_e32 v6, v6
	v_exp_f32_e32 v7, v7
	s_waitcnt lgkmcnt(0)
	v_pk_mul_f32 v[6:7], v[226:227], v[6:7]
	v_cvt_pk_bf16_f32 v6, v6, v7
	v_add_u32_e32 v7, 0x4418, v29
	s_waitcnt lgkmcnt(1)
	v_sub_f32_e32 v8, v23, v228
	v_sub_f32_e32 v9, v22, v229
	v_min_f32_e32 v8, 0x42a00000, v8
	v_min_f32_e32 v9, 0x42a00000, v9
	v_mul_f32_e32 v8, 0x3fb8aa3b, v8
	v_mul_f32_e32 v9, 0x3fb8aa3b, v9
	v_exp_f32_e32 v8, v8
	v_exp_f32_e32 v9, v9
	s_waitcnt lgkmcnt(0)
	v_pk_mul_f32 v[8:9], v[230:231], v[8:9]
	s_nop 0
	v_cvt_pk_bf16_f32 v7, v8, v9
	v_mov_b32_e32 v8, 0
	s_nop 0
	v_mfma_f32_16x16x32_bf16 v[4:7], v[4:7], v[0:3], 0
	s_waitcnt lgkmcnt(0)
	v_mov_b32_e32 v12, v230
	v_mov_b32_e32 v13, v231
	s_and_saveexec_b64 s[2:3], s[36:37]
	v_cmp_gt_u32_e64 s[36:37], v24, v107
	s_nop 5
	v_cndmask_b32_e64 v9, v4, 0, s[36:37]
	v_cmp_lt_u32_e64 s[36:37], v24, v107
	s_nop 1
	v_cndmask_b32_e64 v4, v9, v4, s[36:37]
	v_cndmask_b32_e64 v5, 0, v5, s[36:37]
	v_cmp_le_u32_e64 s[36:37], v31, v107
	s_nop 1
	v_cndmask_b32_e64 v6, 0, v6, s[36:37]
	v_cmp_le_u32_e64 s[36:37], v30, v107
	s_nop 1
	v_cndmask_b32_e64 v7, 0, v7, s[36:37]
	s_or_b64 exec, exec, s[2:3]
	v_mov_b32_e32 v16, 0
	v_mov_b32_e32 v17, 0
	v_mov_b32_e32 v18, 0
	v_mov_b32_e32 v19, 0
	s_and_saveexec_b64 s[4:5], vcc
	s_cbranch_execz .LBB0_222
	v_mad_u32_u24 v9, v10, 33, v15
	v_lshl_add_u32 v9, v9, 2, v105
	ds_read2_b32 v[200:201], v9 offset1:1
	v_add_u32_e32 v199, 0x4400, v9
	ds_read2_b32 v[202:203], v199 offset1:1
	ds_read2_b32 v[204:205], v9 offset0:2 offset1:3
	v_add_u32_e32 v222, 0x4408, v9
	ds_read2_b32 v[220:221], v222 offset1:1
	ds_read2_b32 v[224:225], v9 offset0:4 offset1:5
	v_add_u32_e32 v223, 0x4410, v9
	ds_read2_b32 v[226:227], v223 offset1:1
	ds_read2_b32 v[228:229], v9 offset0:6 offset1:7
	v_add_u32_e32 v232, 0x4418, v9
	ds_read2_b32 v[230:231], v232 offset1:1
	v_add_u32_e32 v14, 0x4410, v9
	v_cmp_eq_u32_e32 vcc, 1, v108
	s_waitcnt lgkmcnt(1)
	v_sub_f32_e32 v10, v26, v200
	v_sub_f32_e32 v11, v25, v201
	v_min_f32_e32 v10, 0x42a00000, v10
	v_min_f32_e32 v11, 0x42a00000, v11
	v_mul_f32_e32 v10, 0x3fb8aa3b, v10
	v_mul_f32_e32 v11, 0x3fb8aa3b, v11
	v_exp_f32_e32 v10, v10
	v_exp_f32_e32 v11, v11
	s_waitcnt lgkmcnt(0)
	v_pk_mul_f32 v[10:11], v[202:203], v[10:11]
	v_cvt_pk_bf16_f32 v10, v10, v11
	v_add_u32_e32 v11, 0x4408, v9
	s_waitcnt lgkmcnt(1)
	v_sub_f32_e32 v12, v28, v204
	v_sub_f32_e32 v13, v27, v205
	v_min_f32_e32 v12, 0x42a00000, v12
	v_min_f32_e32 v13, 0x42a00000, v13
	v_mul_f32_e32 v12, 0x3fb8aa3b, v12
	v_mul_f32_e32 v13, 0x3fb8aa3b, v13
	v_exp_f32_e32 v12, v12
	v_exp_f32_e32 v13, v13
	s_waitcnt lgkmcnt(0)
	v_pk_mul_f32 v[12:13], v[220:221], v[12:13]
	s_nop 0
	v_cvt_pk_bf16_f32 v11, v12, v13
	s_waitcnt lgkmcnt(1)
	v_sub_f32_e32 v12, v21, v224
	v_sub_f32_e32 v13, v20, v225
	v_min_f32_e32 v12, 0x42a00000, v12
	v_min_f32_e32 v13, 0x42a00000, v13
	v_mul_f32_e32 v12, 0x3fb8aa3b, v12
	v_mul_f32_e32 v13, 0x3fb8aa3b, v13
	v_exp_f32_e32 v12, v12
	v_exp_f32_e32 v13, v13
	s_waitcnt lgkmcnt(0)
	v_pk_mul_f32 v[12:13], v[226:227], v[12:13]
	v_cvt_pk_bf16_f32 v12, v12, v13
	v_add_u32_e32 v13, 0x4418, v9
	s_waitcnt lgkmcnt(1)
	v_sub_f32_e32 v9, v23, v228
	v_min_f32_e32 v9, 0x42a00000, v9
	v_mul_f32_e32 v9, 0x3fb8aa3b, v9
	v_exp_f32_e32 v16, v9
	v_sub_f32_e32 v9, v22, v229
	v_min_f32_e32 v9, 0x42a00000, v9
	v_mul_f32_e32 v9, 0x3fb8aa3b, v9
	v_exp_f32_e32 v17, v9
	s_waitcnt lgkmcnt(0)
	v_pk_mul_f32 v[16:17], v[230:231], v[16:17]
	s_nop 0
	v_cvt_pk_bf16_f32 v13, v16, v17
	s_nop 1
	v_mfma_f32_16x16x32_bf16 v[16:19], v[10:13], v[0:3], 0
	s_and_saveexec_b64 s[2:3], vcc
	s_cbranch_execz .LBB0_221
	v_cmp_gt_u32_e32 vcc, v24, v107
	s_nop 4
	v_cndmask_b32_e32 v9, v18, v18, vcc
	v_cndmask_b32_e32 v10, v19, v19, vcc
	v_cndmask_b32_e64 v11, v16, 0, vcc
	v_cmp_lt_u32_e32 vcc, v24, v107
	s_nop 1
	v_cndmask_b32_e32 v16, v11, v16, vcc
	v_cndmask_b32_e32 v10, v10, v19, vcc
	v_cndmask_b32_e32 v9, v9, v18, vcc
	v_cndmask_b32_e32 v17, 0, v17, vcc
	v_cmp_le_u32_e32 vcc, v31, v107
	s_nop 1
	v_cndmask_b32_e32 v18, 0, v9, vcc
	v_cmp_le_u32_e32 vcc, v30, v107
	s_nop 1
	v_cndmask_b32_e32 v19, 0, v10, vcc

.LBB0_222:
	s_or_b64 exec, exec, s[4:5]
	v_cmp_lt_u32_e32 vcc, 1, v108
	v_mov_b32_e32 v9, 0
	v_mov_b32_e32 v10, 0
	v_mov_b32_e32 v11, 0
	s_and_saveexec_b64 s[4:5], vcc
	s_cbranch_execz .LBB0_226
	v_add_u32_e32 v8, 0x1080, v29
	ds_read2_b32 v[200:201], v8 offset1:1
	v_add_u32_e32 v199, 0x5480, v29
	ds_read2_b32 v[202:203], v199 offset1:1
	v_add_u32_e32 v220, 0x1088, v29
	ds_read2_b32 v[204:205], v220 offset1:1
	v_add_u32_e32 v221, 0x5488, v29
	ds_read2_b32 v[222:223], v221 offset1:1
	v_add_u32_e32 v226, 0x1090, v29
	ds_read2_b32 v[224:225], v226 offset1:1
	v_add_u32_e32 v227, 0x5490, v29
	ds_read2_b32 v[228:229], v227 offset1:1
	v_add_u32_e32 v232, 0x1098, v29
	ds_read2_b32 v[230:231], v232 offset1:1
	v_add_u32_e32 v233, 0x5498, v29
	ds_read2_b32 v[234:235], v233 offset1:1
	v_cmp_eq_u32_e64 s[36:37], 2, v108
	s_waitcnt lgkmcnt(1)
	v_sub_f32_e32 v8, v26, v200
	v_sub_f32_e32 v9, v25, v201
	v_min_f32_e32 v8, 0x42a00000, v8
	v_min_f32_e32 v9, 0x42a00000, v9
	v_mul_f32_e32 v8, 0x3fb8aa3b, v8
	v_mul_f32_e32 v9, 0x3fb8aa3b, v9
	v_exp_f32_e32 v8, v8
	v_exp_f32_e32 v9, v9
	s_waitcnt lgkmcnt(0)
	v_pk_mul_f32 v[8:9], v[202:203], v[8:9]
	s_nop 0
	v_cvt_pk_bf16_f32 v8, v8, v9
	v_add_u32_e32 v9, 0x1088, v29
	s_waitcnt lgkmcnt(0)
	v_sub_f32_e32 v9, v28, v204
	v_min_f32_e32 v9, 0x42a00000, v9
	v_mul_f32_e32 v9, 0x3fb8aa3b, v9
	v_exp_f32_e32 v10, v9
	v_sub_f32_e32 v9, v27, v205
	v_min_f32_e32 v9, 0x42a00000, v9
	v_mul_f32_e32 v9, 0x3fb8aa3b, v9
	v_exp_f32_e32 v11, v9
	v_add_u32_e32 v9, 0x5488, v29
	s_waitcnt lgkmcnt(0)
	v_pk_mul_f32 v[10:11], v[222:223], v[10:11]
	s_nop 0
	v_cvt_pk_bf16_f32 v9, v10, v11
	s_waitcnt lgkmcnt(1)
	v_sub_f32_e32 v10, v21, v224
	v_sub_f32_e32 v11, v20, v225
	v_min_f32_e32 v10, 0x42a00000, v10
	v_min_f32_e32 v11, 0x42a00000, v11
	v_mul_f32_e32 v10, 0x3fb8aa3b, v10
	v_mul_f32_e32 v11, 0x3fb8aa3b, v11
	v_exp_f32_e32 v10, v10
	v_exp_f32_e32 v11, v11
	s_waitcnt lgkmcnt(0)
	v_pk_mul_f32 v[10:11], v[228:229], v[10:11]
	s_nop 0
	v_cvt_pk_bf16_f32 v10, v10, v11
	v_add_u32_e32 v11, 0x1098, v29
	s_waitcnt lgkmcnt(0)
	v_sub_f32_e32 v11, v23, v230
	v_min_f32_e32 v11, 0x42a00000, v11
	v_mul_f32_e32 v11, 0x3fb8aa3b, v11
	v_exp_f32_e32 v12, v11
	v_sub_f32_e32 v11, v22, v231
	v_min_f32_e32 v11, 0x42a00000, v11
	v_mul_f32_e32 v11, 0x3fb8aa3b, v11
	v_exp_f32_e32 v13, v11
	v_add_u32_e32 v11, 0x5498, v29
	s_waitcnt lgkmcnt(0)
	v_pk_mul_f32 v[12:13], v[234:235], v[12:13]
	s_nop 0
	v_cvt_pk_bf16_f32 v11, v12, v13
	s_nop 1
	v_mfma_f32_16x16x32_bf16 v[8:11], v[8:11], v[0:3], 0
	s_waitcnt lgkmcnt(0)
	v_mov_b32_e32 v32, v234
	v_mov_b32_e32 v33, v235
	s_and_saveexec_b64 s[2:3], s[36:37]
	s_cbranch_execz .LBB0_225
	v_cmp_gt_u32_e64 s[36:37], v24, v107
	s_nop 4
	v_cndmask_b32_e64 v12, v10, v10, s[36:37]
	v_cndmask_b32_e64 v13, v11, v11, s[36:37]
	v_cndmask_b32_e64 v14, v8, 0, s[36:37]
	v_cmp_lt_u32_e64 s[36:37], v24, v107
	s_nop 1
	v_cndmask_b32_e64 v8, v14, v8, s[36:37]
	v_cndmask_b32_e64 v11, v13, v11, s[36:37]
	v_cndmask_b32_e64 v10, v12, v10, s[36:37]
	v_cndmask_b32_e64 v9, 0, v9, s[36:37]
	v_cmp_le_u32_e64 s[36:37], v31, v107
	s_nop 1
	v_cndmask_b32_e64 v10, 0, v10, s[36:37]
	v_cmp_le_u32_e64 s[36:37], v30, v107
	s_nop 1
	v_cndmask_b32_e64 v11, 0, v11, s[36:37]

.LBB0_244:
	s_or_b64 exec, exec, s[2:3]
	s_movk_i32 s2, 0x1040
	v_mad_u32_u24 v23, v27, s2, v28
	v_add_u32_e32 v8, 0xfffffefc, v23
	v_cmp_eq_u32_e64 s[36:37], 0, v27
	v_cmp_ne_u32_e32 vcc, 0, v27
	v_mov_b32_e32 v32, 0
	v_lshl_add_u32 v50, v29, 2, v8
	v_mov_b32_e32 v33, 0
	s_and_saveexec_b64 s[2:3], vcc
	ds_read_b32 v33, v50
	s_or_b64 exec, exec, s[2:3]
	v_lshlrev_b32_e32 v49, 2, v29
	s_and_saveexec_b64 s[2:3], vcc
	s_movk_i32 s4, 0xff00
	v_add3_u32 v8, v23, v49, s4
	ds_read_b32 v32, v8
	s_or_b64 exec, exec, s[2:3]
	v_mul_u32_u24_e32 v8, 0x104, v19
	v_add3_u32 v22, v28, v8, v49
	ds_read2_b32 v[8:9], v22 offset1:1
	v_mov_b32_e32 v36, 0
	v_mov_b32_e32 v38, 0
	s_and_saveexec_b64 s[2:3], vcc
	ds_read_b32 v38, v50 offset:8
	s_or_b64 exec, exec, s[2:3]
	s_and_saveexec_b64 s[2:3], vcc
	s_movk_i32 s4, 0xff08
	v_add3_u32 v10, v23, v49, s4
	ds_read_b32 v36, v10
	s_or_b64 exec, exec, s[2:3]
	ds_read2_b32 v[10:11], v22 offset0:2 offset1:3
	v_mov_b32_e32 v39, 0
	v_mov_b32_e32 v42, 0
	s_and_saveexec_b64 s[2:3], vcc
	ds_read_b32 v42, v50 offset:16
	s_or_b64 exec, exec, s[2:3]
	s_and_saveexec_b64 s[2:3], vcc
	s_movk_i32 s4, 0xff10
	v_add3_u32 v12, v23, v49, s4
	ds_read_b32 v39, v12
	s_or_b64 exec, exec, s[2:3]
	ds_read2_b32 v[12:13], v22 offset0:4 offset1:5
	v_mov_b32_e32 v44, 0
	v_mov_b32_e32 v46, 0
	s_and_saveexec_b64 s[2:3], vcc
	ds_read_b32 v46, v50 offset:24
	s_or_b64 exec, exec, s[2:3]
	s_and_saveexec_b64 s[2:3], vcc
	s_movk_i32 s4, 0xff18
	v_add3_u32 v14, v23, v49, s4
	ds_read_b32 v44, v14
	s_or_b64 exec, exec, s[2:3]
	ds_read2_b32 v[14:15], v22 offset0:6 offset1:7
	v_mov_b32_e32 v34, 0
	v_mov_b32_e32 v35, 0
	s_and_saveexec_b64 s[2:3], vcc
	ds_read_b32 v35, v50 offset:128
	s_or_b64 exec, exec, s[2:3]
	s_and_saveexec_b64 s[2:3], vcc
	s_movk_i32 s4, 0xff80
	v_add3_u32 v16, v23, v49, s4
	ds_read_b32 v34, v16
	s_or_b64 exec, exec, s[2:3]
	ds_read2_b32 v[16:17], v22 offset0:32 offset1:33
	v_mov_b32_e32 v37, 0
	v_mov_b32_e32 v40, 0
	s_and_saveexec_b64 s[2:3], vcc
	ds_read_b32 v40, v50 offset:136
	s_or_b64 exec, exec, s[2:3]
	s_and_saveexec_b64 s[2:3], vcc
	s_movk_i32 s4, 0xff88
	v_add3_u32 v18, v23, v49, s4
	ds_read_b32 v37, v18
	s_or_b64 exec, exec, s[2:3]
	ds_read2_b32 v[18:19], v22 offset0:34 offset1:35
	v_mov_b32_e32 v41, 0
	v_mov_b32_e32 v43, 0
	s_and_saveexec_b64 s[2:3], vcc
	ds_read_b32 v43, v50 offset:144
	s_or_b64 exec, exec, s[2:3]
	s_and_saveexec_b64 s[2:3], vcc
	s_movk_i32 s4, 0xff90
	v_add3_u32 v20, v23, v49, s4
	ds_read_b32 v41, v20
	s_or_b64 exec, exec, s[2:3]
	ds_read2_b32 v[20:21], v22 offset0:36 offset1:37
	v_mov_b32_e32 v45, 0
	v_mov_b32_e32 v47, 0
	s_and_saveexec_b64 s[2:3], vcc
	ds_read_b32 v47, v50 offset:152
	s_or_b64 exec, exec, s[2:3]
	s_and_saveexec_b64 s[2:3], vcc
	s_movk_i32 s4, 0xff98
	v_add3_u32 v23, v23, v49, s4
	ds_read_b32 v45, v23
	s_or_b64 exec, exec, s[2:3]
	s_waitcnt lgkmcnt(2)
	v_sub_f32_e32 v23, v16, v35
	v_mul_f32_e32 v23, 0x3fb8aa3b, v23
	v_exp_f32_e32 v52, v23
	v_sub_f32_e32 v23, v17, v34
	v_mul_f32_e32 v16, 0x3fb8aa3b, v16
	v_mul_f32_e32 v17, 0x3fb8aa3b, v17
	v_exp_f32_e32 v16, v16
	v_exp_f32_e32 v17, v17
	v_mul_f32_e32 v23, 0x3fb8aa3b, v23
	v_exp_f32_e32 v53, v23
	v_lshlrev_b32_e32 v54, 16, v0
	v_and_b32_e32 v55, 0xffff0000, v0
	v_pk_mul_f32 v[16:17], v[16:17], v[54:55]
	v_pk_mul_f32 v[52:53], v[52:53], v[54:55]
	v_cvt_pk_bf16_f32 v16, v16, v17
	s_waitcnt lgkmcnt(1)
	v_sub_f32_e32 v17, v18, v40
	v_mul_f32_e32 v17, 0x3fb8aa3b, v17
	v_cvt_pk_bf16_f32 v0, v52, v53
	v_exp_f32_e32 v52, v17
	v_sub_f32_e32 v17, v19, v37
	v_mul_f32_e32 v17, 0x3fb8aa3b, v17
	v_exp_f32_e32 v53, v17
	v_mul_f32_e32 v17, 0x3fb8aa3b, v18
	v_exp_f32_e32 v18, v17
	v_mul_f32_e32 v17, 0x3fb8aa3b, v19
	v_exp_f32_e32 v19, v17
	v_lshlrev_b32_e32 v54, 16, v1
	v_and_b32_e32 v55, 0xffff0000, v1
	v_pk_mul_f32 v[52:53], v[52:53], v[54:55]
	v_pk_mul_f32 v[18:19], v[18:19], v[54:55]
	v_cvt_pk_bf16_f32 v1, v52, v53
	v_cvt_pk_bf16_f32 v17, v18, v19
	s_waitcnt lgkmcnt(0)
	v_sub_f32_e32 v18, v20, v43
	v_sub_f32_e32 v19, v21, v41
	v_mul_f32_e32 v18, 0x3fb8aa3b, v18
	v_mul_f32_e32 v19, 0x3fb8aa3b, v19
	v_exp_f32_e32 v18, v18
	v_exp_f32_e32 v19, v19
	v_mul_f32_e32 v20, 0x3fb8aa3b, v20
	v_mul_f32_e32 v21, 0x3fb8aa3b, v21
	v_exp_f32_e32 v20, v20
	v_exp_f32_e32 v21, v21
	v_lshlrev_b32_e32 v52, 16, v2
	v_and_b32_e32 v53, 0xffff0000, v2
	v_pk_mul_f32 v[18:19], v[18:19], v[52:53]
	s_movk_i32 s4, 0x300
	v_cvt_pk_bf16_f32 v2, v18, v19
	v_pk_mul_f32 v[18:19], v[20:21], v[52:53]
	v_lshlrev_b32_e32 v52, 16, v4
	v_cvt_pk_bf16_f32 v18, v18, v19
	v_sub_f32_e32 v19, v8, v33
	v_mul_f32_e32 v19, 0x3fb8aa3b, v19
	v_exp_f32_e32 v20, v19
	v_sub_f32_e32 v19, v9, v32
	v_mul_f32_e32 v8, 0x3fb8aa3b, v8
	v_mul_f32_e32 v9, 0x3fb8aa3b, v9
	v_exp_f32_e32 v8, v8
	v_exp_f32_e32 v9, v9
	v_mul_f32_e32 v19, 0x3fb8aa3b, v19
	v_exp_f32_e32 v21, v19
	v_and_b32_e32 v53, 0xffff0000, v4
	v_pk_mul_f32 v[8:9], v[8:9], v[52:53]
	v_or_b32_e32 v50, 2, v30
	v_cvt_pk_bf16_f32 v8, v8, v9
	v_sub_f32_e32 v9, v10, v38
	v_pk_mul_f32 v[20:21], v[20:21], v[52:53]
	v_mul_f32_e32 v9, 0x3fb8aa3b, v9
	v_cvt_pk_bf16_f32 v4, v20, v21
	v_exp_f32_e32 v20, v9
	v_sub_f32_e32 v9, v11, v36
	v_mul_f32_e32 v9, 0x3fb8aa3b, v9
	v_exp_f32_e32 v21, v9
	v_mul_f32_e32 v9, 0x3fb8aa3b, v10
	v_exp_f32_e32 v10, v9
	v_mul_f32_e32 v9, 0x3fb8aa3b, v11
	v_exp_f32_e32 v11, v9
	v_lshlrev_b32_e32 v52, 16, v5
	v_and_b32_e32 v53, 0xffff0000, v5
	v_pk_mul_f32 v[20:21], v[20:21], v[52:53]
	v_pk_mul_f32 v[10:11], v[10:11], v[52:53]
	v_cvt_pk_bf16_f32 v5, v20, v21
	v_cvt_pk_bf16_f32 v9, v10, v11
	v_sub_f32_e32 v10, v12, v42
	v_sub_f32_e32 v11, v13, v39
	v_mul_f32_e32 v10, 0x3fb8aa3b, v10
	v_mul_f32_e32 v11, 0x3fb8aa3b, v11
	v_exp_f32_e32 v10, v10
	v_exp_f32_e32 v11, v11
	v_mul_f32_e32 v12, 0x3fb8aa3b, v12
	v_mul_f32_e32 v13, 0x3fb8aa3b, v13
	v_exp_f32_e32 v12, v12
	v_exp_f32_e32 v13, v13
	v_lshlrev_b32_e32 v20, 16, v6
	v_and_b32_e32 v21, 0xffff0000, v6
	v_pk_mul_f32 v[10:11], v[10:11], v[20:21]
	v_or_b32_e32 v49, 3, v30
	v_cvt_pk_bf16_f32 v6, v10, v11
	v_pk_mul_f32 v[10:11], v[12:13], v[20:21]
	v_lshlrev_b32_e32 v20, 16, v7
	v_cvt_pk_bf16_f32 v10, v10, v11
	v_sub_f32_e32 v11, v14, v46
	v_mul_f32_e32 v11, 0x3fb8aa3b, v11
	v_exp_f32_e32 v12, v11
	v_sub_f32_e32 v11, v15, v44
	v_mul_f32_e32 v11, 0x3fb8aa3b, v11
	v_exp_f32_e32 v13, v11
	v_mul_f32_e32 v11, 0x3fb8aa3b, v14
	v_exp_f32_e32 v14, v11
	v_mul_f32_e32 v11, 0x3fb8aa3b, v15
	v_exp_f32_e32 v15, v11
	v_and_b32_e32 v21, 0xffff0000, v7
	v_pk_mul_f32 v[12:13], v[12:13], v[20:21]
	s_nop 0
	v_cvt_pk_bf16_f32 v7, v12, v13
	v_pk_mul_f32 v[12:13], v[14:15], v[20:21]
	v_lshlrev_b32_e32 v20, 16, v3
	v_cvt_pk_bf16_f32 v11, v12, v13
	ds_read2_b32 v[12:13], v22 offset0:38 offset1:39
	v_and_b32_e32 v21, 0xffff0000, v3
	s_waitcnt lgkmcnt(0)
	v_sub_f32_e32 v14, v12, v47
	v_sub_f32_e32 v15, v13, v45
	v_mul_f32_e32 v12, 0x3fb8aa3b, v12
	v_mul_f32_e32 v13, 0x3fb8aa3b, v13
	v_exp_f32_e32 v12, v12
	v_exp_f32_e32 v13, v13
	v_mul_f32_e32 v14, 0x3fb8aa3b, v14
	v_mul_f32_e32 v15, 0x3fb8aa3b, v15
	v_exp_f32_e32 v14, v14
	v_exp_f32_e32 v15, v15
	v_pk_mul_f32 v[12:13], v[12:13], v[20:21]
	v_pk_mul_f32 v[14:15], v[14:15], v[20:21]
	v_cvt_pk_bf16_f32 v19, v12, v13
	v_mov_b64_e32 v[12:13], s[64:65]
	v_mad_u64_u32 v[12:13], s[2:3], v24, s4, v[12:13]
	v_cvt_pk_bf16_f32 v3, v14, v15
	v_mov_b32_e32 v14, v13
	v_mad_u64_u32 v[14:15], s[2:3], v25, s4, v[14:15]
	v_mov_b32_e32 v13, v14
	v_lshl_add_u64 v[12:13], v[12:13], 0, v[176:177]
	v_lshlrev_b32_e32 v14, 1, v29
	v_mov_b32_e32 v15, v177
	v_lshl_add_u64 v[12:13], v[12:13], 0, v[14:15]
	s_movk_i32 s2, 0x41
	global_store_dwordx4 v[12:13], v[8:11], off sc1
	global_store_dwordx4 v[12:13], v[16:19], off offset:64 sc1
	s_nop 0
	v_mad_u32_u24 v8, v26, s2, v29
	v_lshl_add_u32 v15, v8, 2, v28
	ds_read2_b32 v[80:81], v15 offset1:1
	v_add_u32_e32 v84, 0x4400, v15
	ds_read2_b32 v[82:83], v84 offset1:1
	ds_read2_b32 v[86:87], v15 offset0:2 offset1:3
	v_add_u32_e32 v85, 0x4408, v15
	ds_read2_b32 v[88:89], v85 offset1:1
	ds_read2_b32 v[90:91], v15 offset0:4 offset1:5
	v_add_u32_e32 v94, 0x4410, v15
	ds_read2_b32 v[92:93], v94 offset1:1
	ds_read2_b32 v[96:97], v15 offset0:6 offset1:7
	v_add_u32_e32 v95, 0x4418, v15
	ds_read2_b32 v[98:99], v95 offset1:1
	ds_read2_b32 v[100:101], v15 offset0:32 offset1:33
	v_add_u32_e32 v104, 0x4480, v15
	ds_read2_b32 v[102:103], v104 offset1:1
	ds_read2_b32 v[106:107], v15 offset0:34 offset1:35
	v_add_u32_e32 v105, 0x4488, v15
	ds_read2_b32 v[108:109], v105 offset1:1
	ds_read2_b32 v[110:111], v15 offset0:36 offset1:37
	v_add_u32_e32 v114, 0x4490, v15
	ds_read2_b32 v[112:113], v114 offset1:1
	ds_read2_b32 v[116:117], v15 offset0:38 offset1:39
	v_add_u32_e32 v115, 0x4498, v15
	ds_read2_b32 v[118:119], v115 offset1:1
	v_add_u32_e32 v14, 0x4480, v15
	s_waitcnt lgkmcnt(1)
	v_sub_f32_e32 v8, v33, v80
	v_sub_f32_e32 v9, v32, v81
	v_min_f32_e32 v8, 0x42a00000, v8
	v_min_f32_e32 v9, 0x42a00000, v9
	v_mul_f32_e32 v8, 0x3fb8aa3b, v8
	v_mul_f32_e32 v9, 0x3fb8aa3b, v9
	v_exp_f32_e32 v8, v8
	v_exp_f32_e32 v9, v9
	s_waitcnt lgkmcnt(0)
	v_pk_mul_f32 v[8:9], v[82:83], v[8:9]
	v_cvt_pk_bf16_f32 v8, v8, v9
	v_add_u32_e32 v9, 0x4408, v15
	s_waitcnt lgkmcnt(1)
	v_sub_f32_e32 v10, v38, v86
	v_sub_f32_e32 v11, v36, v87
	v_min_f32_e32 v10, 0x42a00000, v10
	v_min_f32_e32 v11, 0x42a00000, v11
	v_mul_f32_e32 v10, 0x3fb8aa3b, v10
	v_mul_f32_e32 v11, 0x3fb8aa3b, v11
	v_exp_f32_e32 v10, v10
	v_exp_f32_e32 v11, v11
	s_waitcnt lgkmcnt(0)
	v_pk_mul_f32 v[10:11], v[88:89], v[10:11]
	s_nop 0
	v_cvt_pk_bf16_f32 v9, v10, v11
	s_waitcnt lgkmcnt(1)
	v_sub_f32_e32 v10, v42, v90
	v_sub_f32_e32 v11, v39, v91
	v_min_f32_e32 v10, 0x42a00000, v10
	v_min_f32_e32 v11, 0x42a00000, v11
	v_mul_f32_e32 v10, 0x3fb8aa3b, v10
	v_mul_f32_e32 v11, 0x3fb8aa3b, v11
	v_exp_f32_e32 v10, v10
	v_exp_f32_e32 v11, v11
	s_waitcnt lgkmcnt(0)
	v_pk_mul_f32 v[10:11], v[92:93], v[10:11]
	v_cvt_pk_bf16_f32 v10, v10, v11
	v_add_u32_e32 v11, 0x4418, v15
	s_waitcnt lgkmcnt(1)
	v_sub_f32_e32 v12, v46, v96
	v_sub_f32_e32 v13, v44, v97
	v_min_f32_e32 v12, 0x42a00000, v12
	v_min_f32_e32 v13, 0x42a00000, v13
	v_mul_f32_e32 v12, 0x3fb8aa3b, v12
	v_mul_f32_e32 v13, 0x3fb8aa3b, v13
	v_exp_f32_e32 v12, v12
	v_exp_f32_e32 v13, v13
	s_waitcnt lgkmcnt(0)
	v_pk_mul_f32 v[12:13], v[98:99], v[12:13]
	s_nop 0
	v_cvt_pk_bf16_f32 v11, v12, v13
	s_nop 1
	v_mfma_f32_16x16x32_bf16 v[8:11], v[8:11], v[4:7], 0
	s_waitcnt lgkmcnt(1)
	v_sub_f32_e32 v12, v35, v100
	v_sub_f32_e32 v13, v34, v101
	v_min_f32_e32 v12, 0x42a00000, v12
	v_min_f32_e32 v13, 0x42a00000, v13
	v_mul_f32_e32 v12, 0x3fb8aa3b, v12
	v_mul_f32_e32 v13, 0x3fb8aa3b, v13
	v_exp_f32_e32 v12, v12
	v_exp_f32_e32 v13, v13
	s_waitcnt lgkmcnt(0)
	v_pk_mul_f32 v[12:13], v[102:103], v[12:13]
	v_cvt_pk_bf16_f32 v12, v12, v13
	v_add_u32_e32 v13, 0x4488, v15
	s_waitcnt lgkmcnt(1)
	v_sub_f32_e32 v14, v40, v106
	v_min_f32_e32 v14, 0x42a00000, v14
	v_mul_f32_e32 v14, 0x3fb8aa3b, v14
	v_exp_f32_e32 v16, v14
	v_sub_f32_e32 v14, v37, v107
	v_min_f32_e32 v14, 0x42a00000, v14
	v_mul_f32_e32 v14, 0x3fb8aa3b, v14
	v_exp_f32_e32 v17, v14
	v_add_u32_e32 v14, 0x4490, v15
	s_waitcnt lgkmcnt(0)
	v_pk_mul_f32 v[16:17], v[108:109], v[16:17]
	s_nop 0
	v_cvt_pk_bf16_f32 v13, v16, v17
	s_waitcnt lgkmcnt(1)
	v_sub_f32_e32 v16, v43, v110
	v_sub_f32_e32 v17, v41, v111
	v_min_f32_e32 v16, 0x42a00000, v16
	v_min_f32_e32 v17, 0x42a00000, v17
	v_mul_f32_e32 v16, 0x3fb8aa3b, v16
	v_mul_f32_e32 v17, 0x3fb8aa3b, v17
	v_exp_f32_e32 v16, v16
	v_exp_f32_e32 v17, v17
	s_waitcnt lgkmcnt(0)
	v_pk_mul_f32 v[16:17], v[112:113], v[16:17]
	s_nop 0
	v_cvt_pk_bf16_f32 v14, v16, v17
	s_waitcnt lgkmcnt(1)
	v_sub_f32_e32 v15, v47, v116
	v_min_f32_e32 v15, 0x42a00000, v15
	v_mul_f32_e32 v15, 0x3fb8aa3b, v15
	v_exp_f32_e32 v16, v15
	v_sub_f32_e32 v15, v45, v117
	v_min_f32_e32 v15, 0x42a00000, v15
	v_mul_f32_e32 v15, 0x3fb8aa3b, v15
	v_exp_f32_e32 v17, v15
	s_waitcnt lgkmcnt(0)
	v_pk_mul_f32 v[16:17], v[118:119], v[16:17]
	s_nop 0
	v_cvt_pk_bf16_f32 v15, v16, v17
	v_mov_b32_e32 v16, 0
	s_nop 0
	v_mfma_f32_16x16x32_bf16 v[8:11], v[12:15], v[0:3], v[8:11]
	s_waitcnt lgkmcnt(0)
	v_mov_b32_e32 v18, v118
	v_mov_b32_e32 v19, v119
	s_and_saveexec_b64 s[2:3], s[36:37]
	v_cmp_gt_u32_e64 s[36:37], v30, v26
	s_nop 5
	v_cndmask_b32_e64 v12, v8, 0, s[36:37]
	v_cmp_lt_u32_e64 s[36:37], v30, v26
	s_nop 1
	v_cndmask_b32_e64 v8, v12, v8, s[36:37]
	v_cndmask_b32_e64 v9, 0, v9, s[36:37]
	v_cmp_le_u32_e64 s[36:37], v50, v26
	s_nop 1
	v_cndmask_b32_e64 v10, 0, v10, s[36:37]
	v_cmp_le_u32_e64 s[36:37], v49, v26
	s_nop 1
	v_cndmask_b32_e64 v11, 0, v11, s[36:37]
	s_or_b64 exec, exec, s[2:3]
	v_mov_b32_e32 v20, 0
	v_mov_b32_e32 v21, 0
	v_mov_b32_e32 v22, 0
	v_mov_b32_e32 v23, 0
	s_and_saveexec_b64 s[4:5], vcc
	s_cbranch_execz .LBB0_282
	s_movk_i32 s2, 0x41
	v_mad_u32_u24 v12, v51, s2, v29
	v_lshl_add_u32 v17, v12, 2, v28
	ds_read2_b32 v[80:81], v17 offset1:1
	v_add_u32_e32 v84, 0x4400, v17
	ds_read2_b32 v[82:83], v84 offset1:1
	ds_read2_b32 v[86:87], v17 offset0:2 offset1:3
	v_add_u32_e32 v85, 0x4408, v17
	ds_read2_b32 v[88:89], v85 offset1:1
	ds_read2_b32 v[90:91], v17 offset0:4 offset1:5
	v_add_u32_e32 v94, 0x4410, v17
	ds_read2_b32 v[92:93], v94 offset1:1
	ds_read2_b32 v[96:97], v17 offset0:6 offset1:7
	v_add_u32_e32 v95, 0x4418, v17
	ds_read2_b32 v[98:99], v95 offset1:1
	ds_read2_b32 v[100:101], v17 offset0:32 offset1:33
	v_add_u32_e32 v104, 0x4480, v17
	ds_read2_b32 v[102:103], v104 offset1:1
	ds_read2_b32 v[106:107], v17 offset0:34 offset1:35
	v_add_u32_e32 v105, 0x4488, v17
	ds_read2_b32 v[108:109], v105 offset1:1
	ds_read2_b32 v[110:111], v17 offset0:36 offset1:37
	v_add_u32_e32 v114, 0x4490, v17
	ds_read2_b32 v[112:113], v114 offset1:1
	ds_read2_b32 v[116:117], v17 offset0:38 offset1:39
	v_add_u32_e32 v115, 0x4498, v17
	ds_read2_b32 v[118:119], v115 offset1:1
	v_cmp_eq_u32_e32 vcc, 1, v27
	s_waitcnt lgkmcnt(1)
	v_sub_f32_e32 v12, v33, v80
	v_sub_f32_e32 v13, v32, v81
	v_min_f32_e32 v12, 0x42a00000, v12
	v_min_f32_e32 v13, 0x42a00000, v13
	v_mul_f32_e32 v12, 0x3fb8aa3b, v12
	v_mul_f32_e32 v13, 0x3fb8aa3b, v13
	v_exp_f32_e32 v12, v12
	v_exp_f32_e32 v13, v13
	s_waitcnt lgkmcnt(0)
	v_pk_mul_f32 v[12:13], v[82:83], v[12:13]
	v_cvt_pk_bf16_f32 v12, v12, v13
	v_add_u32_e32 v13, 0x4408, v17
	s_waitcnt lgkmcnt(1)
	v_sub_f32_e32 v14, v38, v86
	v_sub_f32_e32 v15, v36, v87
	v_min_f32_e32 v14, 0x42a00000, v14
	v_min_f32_e32 v15, 0x42a00000, v15
	v_mul_f32_e32 v14, 0x3fb8aa3b, v14
	v_mul_f32_e32 v15, 0x3fb8aa3b, v15
	v_exp_f32_e32 v14, v14
	v_exp_f32_e32 v15, v15
	s_waitcnt lgkmcnt(0)
	v_pk_mul_f32 v[14:15], v[88:89], v[14:15]
	s_nop 0
	v_cvt_pk_bf16_f32 v13, v14, v15
	s_waitcnt lgkmcnt(1)
	v_sub_f32_e32 v14, v42, v90
	v_sub_f32_e32 v15, v39, v91
	v_min_f32_e32 v14, 0x42a00000, v14
	v_min_f32_e32 v15, 0x42a00000, v15
	v_mul_f32_e32 v14, 0x3fb8aa3b, v14
	v_mul_f32_e32 v15, 0x3fb8aa3b, v15
	v_exp_f32_e32 v14, v14
	v_exp_f32_e32 v15, v15
	s_waitcnt lgkmcnt(0)
	v_pk_mul_f32 v[14:15], v[92:93], v[14:15]
	v_cvt_pk_bf16_f32 v14, v14, v15
	v_add_u32_e32 v15, 0x4418, v17
	s_waitcnt lgkmcnt(1)
	v_sub_f32_e32 v18, v46, v96
	v_sub_f32_e32 v19, v44, v97
	v_min_f32_e32 v18, 0x42a00000, v18
	v_min_f32_e32 v19, 0x42a00000, v19
	v_mul_f32_e32 v18, 0x3fb8aa3b, v18
	v_mul_f32_e32 v19, 0x3fb8aa3b, v19
	v_exp_f32_e32 v18, v18
	v_exp_f32_e32 v19, v19
	s_waitcnt lgkmcnt(0)
	v_pk_mul_f32 v[18:19], v[98:99], v[18:19]
	s_nop 0
	v_cvt_pk_bf16_f32 v15, v18, v19
	s_nop 1
	v_mfma_f32_16x16x32_bf16 v[12:15], v[12:15], v[4:7], 0
	s_waitcnt lgkmcnt(1)
	v_sub_f32_e32 v18, v35, v100
	v_sub_f32_e32 v19, v34, v101
	v_min_f32_e32 v18, 0x42a00000, v18
	v_min_f32_e32 v19, 0x42a00000, v19
	v_mul_f32_e32 v18, 0x3fb8aa3b, v18
	v_mul_f32_e32 v19, 0x3fb8aa3b, v19
	v_exp_f32_e32 v18, v18
	v_exp_f32_e32 v19, v19
	s_waitcnt lgkmcnt(0)
	v_pk_mul_f32 v[18:19], v[102:103], v[18:19]
	v_cvt_pk_bf16_f32 v18, v18, v19
	v_add_u32_e32 v19, 0x4488, v17
	s_waitcnt lgkmcnt(1)
	v_sub_f32_e32 v20, v40, v106
	v_sub_f32_e32 v21, v37, v107
	v_min_f32_e32 v20, 0x42a00000, v20
	v_min_f32_e32 v21, 0x42a00000, v21
	v_mul_f32_e32 v20, 0x3fb8aa3b, v20
	v_mul_f32_e32 v21, 0x3fb8aa3b, v21
	v_exp_f32_e32 v20, v20
	v_exp_f32_e32 v21, v21
	s_waitcnt lgkmcnt(0)
	v_pk_mul_f32 v[20:21], v[108:109], v[20:21]
	s_nop 0
	v_cvt_pk_bf16_f32 v19, v20, v21
	s_waitcnt lgkmcnt(1)
	v_sub_f32_e32 v20, v43, v110
	v_sub_f32_e32 v21, v41, v111
	v_min_f32_e32 v20, 0x42a00000, v20
	v_min_f32_e32 v21, 0x42a00000, v21
	v_mul_f32_e32 v20, 0x3fb8aa3b, v20
	v_mul_f32_e32 v21, 0x3fb8aa3b, v21
	v_exp_f32_e32 v20, v20
	v_exp_f32_e32 v21, v21
	s_waitcnt lgkmcnt(0)
	v_pk_mul_f32 v[20:21], v[112:113], v[20:21]
	v_cvt_pk_bf16_f32 v20, v20, v21
	v_add_u32_e32 v21, 0x4498, v17
	s_waitcnt lgkmcnt(1)
	v_sub_f32_e32 v17, v47, v116
	v_min_f32_e32 v17, 0x42a00000, v17
	v_mul_f32_e32 v17, 0x3fb8aa3b, v17
	v_exp_f32_e32 v22, v17
	v_sub_f32_e32 v17, v45, v117
	v_min_f32_e32 v17, 0x42a00000, v17
	v_mul_f32_e32 v17, 0x3fb8aa3b, v17
	v_exp_f32_e32 v23, v17
	s_waitcnt lgkmcnt(0)
	v_pk_mul_f32 v[22:23], v[118:119], v[22:23]
	s_nop 0
	v_cvt_pk_bf16_f32 v21, v22, v23
	s_nop 1
	v_mfma_f32_16x16x32_bf16 v[20:23], v[18:21], v[0:3], v[12:15]
	s_waitcnt lgkmcnt(0)
	v_mov_b32_e32 v52, v118
	v_mov_b32_e32 v53, v119
	s_and_saveexec_b64 s[2:3], vcc
	v_cmp_gt_u32_e32 vcc, v30, v26
	s_nop 5
	v_cndmask_b32_e64 v12, v20, 0, vcc
	v_cmp_lt_u32_e32 vcc, v30, v26
	s_nop 1
	v_cndmask_b32_e32 v20, v12, v20, vcc
	v_cndmask_b32_e32 v21, 0, v21, vcc
	v_cmp_le_u32_e32 vcc, v50, v26
	s_nop 1
	v_cndmask_b32_e32 v22, 0, v22, vcc
	v_cmp_le_u32_e32 vcc, v49, v26
	s_nop 1
	v_cndmask_b32_e32 v23, 0, v23, vcc
	s_or_b64 exec, exec, s[2:3]
.LBB0_282:
	s_or_b64 exec, exec, s[4:5]
	v_cmp_lt_u32_e32 vcc, 1, v27
	v_mov_b32_e32 v17, 0
	v_mov_b32_e32 v18, 0
	v_mov_b32_e32 v19, 0
	s_and_saveexec_b64 s[4:5], vcc
	s_cbranch_execz .LBB0_286
	s_movk_i32 s2, 0x41
	v_mad_u32_u24 v12, v48, s2, v29
	v_lshl_add_u32 v19, v12, 2, v28
	ds_read2_b32 v[80:81], v19 offset1:1
	v_add_u32_e32 v84, 0x4400, v19
	ds_read2_b32 v[82:83], v84 offset1:1
	ds_read2_b32 v[86:87], v19 offset0:2 offset1:3
	v_add_u32_e32 v85, 0x4408, v19
	ds_read2_b32 v[88:89], v85 offset1:1
	ds_read2_b32 v[90:91], v19 offset0:4 offset1:5
	v_add_u32_e32 v94, 0x4410, v19
	ds_read2_b32 v[92:93], v94 offset1:1
	ds_read2_b32 v[96:97], v19 offset0:6 offset1:7
	v_add_u32_e32 v95, 0x4418, v19
	ds_read2_b32 v[98:99], v95 offset1:1
	ds_read2_b32 v[100:101], v19 offset0:32 offset1:33
	v_add_u32_e32 v104, 0x4480, v19
	ds_read2_b32 v[102:103], v104 offset1:1
	ds_read2_b32 v[106:107], v19 offset0:34 offset1:35
	v_add_u32_e32 v105, 0x4488, v19
	ds_read2_b32 v[108:109], v105 offset1:1
	ds_read2_b32 v[110:111], v19 offset0:36 offset1:37
	v_add_u32_e32 v114, 0x4490, v19
	ds_read2_b32 v[112:113], v114 offset1:1
	ds_read2_b32 v[116:117], v19 offset0:38 offset1:39
	v_add_u32_e32 v115, 0x4498, v19
	ds_read2_b32 v[118:119], v115 offset1:1
	v_add_u32_e32 v18, 0x4480, v19
	v_cmp_eq_u32_e64 s[36:37], 2, v27
	s_waitcnt lgkmcnt(1)
	v_sub_f32_e32 v12, v33, v80
	v_sub_f32_e32 v13, v32, v81
	v_min_f32_e32 v12, 0x42a00000, v12
	v_min_f32_e32 v13, 0x42a00000, v13
	v_mul_f32_e32 v12, 0x3fb8aa3b, v12
	v_mul_f32_e32 v13, 0x3fb8aa3b, v13
	v_exp_f32_e32 v12, v12
	v_exp_f32_e32 v13, v13
	s_waitcnt lgkmcnt(0)
	v_pk_mul_f32 v[12:13], v[82:83], v[12:13]
	v_cvt_pk_bf16_f32 v12, v12, v13
	v_add_u32_e32 v13, 0x4408, v19
	s_waitcnt lgkmcnt(1)
	v_sub_f32_e32 v14, v38, v86
	v_sub_f32_e32 v15, v36, v87
	v_min_f32_e32 v14, 0x42a00000, v14
	v_min_f32_e32 v15, 0x42a00000, v15
	v_mul_f32_e32 v14, 0x3fb8aa3b, v14
	v_mul_f32_e32 v15, 0x3fb8aa3b, v15
	v_exp_f32_e32 v14, v14
	v_exp_f32_e32 v15, v15
	s_waitcnt lgkmcnt(0)
	v_pk_mul_f32 v[14:15], v[88:89], v[14:15]
	s_nop 0
	v_cvt_pk_bf16_f32 v13, v14, v15
	s_waitcnt lgkmcnt(1)
	v_sub_f32_e32 v14, v42, v90
	v_sub_f32_e32 v15, v39, v91
	v_min_f32_e32 v14, 0x42a00000, v14
	v_min_f32_e32 v15, 0x42a00000, v15
	v_mul_f32_e32 v14, 0x3fb8aa3b, v14
	v_mul_f32_e32 v15, 0x3fb8aa3b, v15
	v_exp_f32_e32 v14, v14
	v_exp_f32_e32 v15, v15
	s_waitcnt lgkmcnt(0)
	v_pk_mul_f32 v[14:15], v[92:93], v[14:15]
	v_cvt_pk_bf16_f32 v14, v14, v15
	v_add_u32_e32 v15, 0x4418, v19
	s_waitcnt lgkmcnt(1)
	v_sub_f32_e32 v16, v46, v96
	v_sub_f32_e32 v17, v44, v97
	v_min_f32_e32 v16, 0x42a00000, v16
	v_min_f32_e32 v17, 0x42a00000, v17
	v_mul_f32_e32 v16, 0x3fb8aa3b, v16
	v_mul_f32_e32 v17, 0x3fb8aa3b, v17
	v_exp_f32_e32 v16, v16
	v_exp_f32_e32 v17, v17
	s_waitcnt lgkmcnt(0)
	v_pk_mul_f32 v[16:17], v[98:99], v[16:17]
	s_nop 0
	v_cvt_pk_bf16_f32 v15, v16, v17
	s_nop 1
	v_mfma_f32_16x16x32_bf16 v[12:15], v[12:15], v[4:7], 0
	s_waitcnt lgkmcnt(1)
	v_sub_f32_e32 v16, v35, v100
	v_sub_f32_e32 v17, v34, v101
	v_min_f32_e32 v16, 0x42a00000, v16
	v_min_f32_e32 v17, 0x42a00000, v17
	v_mul_f32_e32 v16, 0x3fb8aa3b, v16
	v_mul_f32_e32 v17, 0x3fb8aa3b, v17
	v_exp_f32_e32 v16, v16
	v_exp_f32_e32 v17, v17
	s_waitcnt lgkmcnt(0)
	v_pk_mul_f32 v[16:17], v[102:103], v[16:17]
	v_cvt_pk_bf16_f32 v16, v16, v17
	v_add_u32_e32 v17, 0x4488, v19
	s_waitcnt lgkmcnt(1)
	v_sub_f32_e32 v18, v40, v106
	v_min_f32_e32 v18, 0x42a00000, v18
	v_mul_f32_e32 v18, 0x3fb8aa3b, v18
	v_exp_f32_e32 v52, v18
	v_sub_f32_e32 v18, v37, v107
	v_min_f32_e32 v18, 0x42a00000, v18
	v_mul_f32_e32 v18, 0x3fb8aa3b, v18
	v_exp_f32_e32 v53, v18
	v_add_u32_e32 v18, 0x4490, v19
	s_waitcnt lgkmcnt(0)
	v_pk_mul_f32 v[52:53], v[108:109], v[52:53]
	s_nop 0
	v_cvt_pk_bf16_f32 v17, v52, v53
	s_waitcnt lgkmcnt(1)
	v_sub_f32_e32 v48, v43, v110
	v_min_f32_e32 v48, 0x42a00000, v48
	v_mul_f32_e32 v48, 0x3fb8aa3b, v48
	v_exp_f32_e32 v52, v48
	v_sub_f32_e32 v48, v41, v111
	v_min_f32_e32 v48, 0x42a00000, v48
	v_mul_f32_e32 v48, 0x3fb8aa3b, v48
	v_exp_f32_e32 v53, v48
	v_add_u32_e32 v48, 0x4498, v19
	s_waitcnt lgkmcnt(0)
	v_pk_mul_f32 v[52:53], v[112:113], v[52:53]
	s_nop 0
	v_cvt_pk_bf16_f32 v18, v52, v53
	s_waitcnt lgkmcnt(1)
	v_sub_f32_e32 v19, v47, v116
	v_min_f32_e32 v19, 0x42a00000, v19
	v_mul_f32_e32 v19, 0x3fb8aa3b, v19
	v_exp_f32_e32 v52, v19
	v_sub_f32_e32 v19, v45, v117
	v_min_f32_e32 v19, 0x42a00000, v19
	v_mul_f32_e32 v19, 0x3fb8aa3b, v19
	v_exp_f32_e32 v53, v19
	s_waitcnt lgkmcnt(0)
	v_pk_mul_f32 v[52:53], v[118:119], v[52:53]
	s_nop 0
	v_cvt_pk_bf16_f32 v19, v52, v53
	s_nop 1
	v_mfma_f32_16x16x32_bf16 v[16:19], v[16:19], v[0:3], v[12:15]
	s_waitcnt lgkmcnt(0)
	v_mov_b32_e32 v54, v118
	v_mov_b32_e32 v55, v119
	s_and_saveexec_b64 s[2:3], s[36:37]
	v_cmp_gt_u32_e64 s[36:37], v30, v26
	s_nop 5
	v_cndmask_b32_e64 v12, v16, 0, s[36:37]
	v_cmp_lt_u32_e64 s[36:37], v30, v26
	s_nop 1
	v_cndmask_b32_e64 v16, v12, v16, s[36:37]
	v_cndmask_b32_e64 v17, 0, v17, s[36:37]
	v_cmp_le_u32_e64 s[36:37], v50, v26
	s_nop 1
	v_cndmask_b32_e64 v18, 0, v18, s[36:37]
	v_cmp_le_u32_e64 s[36:37], v49, v26
	s_nop 1
	v_cndmask_b32_e64 v19, 0, v19, s[36:37]
	s_or_b64 exec, exec, s[2:3]
